# stack6 + attention epilogue lane swaps via DPP, half-max published by all lanes inside the softmax stream, softmax over 13 P.V gaps
# baseline (speedup 1.0000x reference)
.Li0_sm:
	ds_read_b64_tr_b16 v[188:189], v158 offset:0x2000
	ds_read_b64_tr_b16 v[190:191], v158 offset:0x2800
	ds_read_b64_tr_b16 v[192:193], v158 offset:0x3000
	ds_read_b64_tr_b16 v[194:195], v158 offset:0x3800
	s_waitcnt lgkmcnt(4)
	s_nop 1
	v_mfma_f32_32x32x16_bf16 v[48:63], v[176:179], v[180:183], v[48:63]
	ds_read_b64_tr_b16 v[180:181], v158 offset:0x200
	ds_read_b64_tr_b16 v[182:183], v158 offset:0xa00
	v_mul_f32_e32 v114, 0xbe0293ee, v166
	v_max_f32_e32 v112, v65, v65
	v_max_f32_e32 v113, v64, v64
	v_fmamk_f32 v64, v64, 0x3e0293ee, v114
	v_max_f32_e32 v112, v113, v112
	v_exp_f32_e32 v64, v64
	v_fmamk_f32 v65, v65, 0x3e0293ee, v114
	v_mfma_f32_32x32x16_bf16 v[48:63], v[124:127], v[184:187], v[48:63]
	ds_read_b64_tr_b16 v[184:185], v158 offset:0x1200
	ds_read_b64_tr_b16 v[186:187], v158 offset:0x1a00
	v_max3_f32 v112, v112, v66, v67
	v_exp_f32_e32 v65, v65
	v_fmamk_f32 v66, v66, 0x3e0293ee, v114
	v_exp_f32_e32 v66, v66
	v_fmamk_f32 v67, v67, 0x3e0293ee, v114
	v_max3_f32 v112, v112, v68, v69
	v_exp_f32_e32 v67, v67
	s_waitcnt lgkmcnt(6)
	v_mfma_f32_32x32x16_bf16 v[48:63], v[172:175], v[188:191], v[48:63]
	ds_read_b64_tr_b16 v[188:189], v158 offset:0x2200
	ds_read_b64_tr_b16 v[190:191], v158 offset:0x2a00
	v_fmamk_f32 v68, v68, 0x3e0293ee, v114
	v_add_f32_e32 v115, 0, v64
	v_exp_f32_e32 v68, v68
	v_fmamk_f32 v69, v69, 0x3e0293ee, v114
	v_max3_f32 v112, v112, v70, v71
	v_add_f32_e32 v115, v65, v115
	v_exp_f32_e32 v69, v69
	s_waitcnt lgkmcnt(6)
	v_mfma_f32_32x32x16_bf16 v[48:63], v[168:171], v[192:195], v[48:63]
	ds_read_b64_tr_b16 v[192:193], v158 offset:0x3200
	ds_read_b64_tr_b16 v[194:195], v158 offset:0x3a00
	v_fmamk_f32 v70, v70, 0x3e0293ee, v114
	v_add_f32_e32 v115, v66, v115
	v_exp_f32_e32 v70, v70
	v_fmamk_f32 v71, v71, 0x3e0293ee, v114
	v_max3_f32 v112, v112, v72, v73
	v_add_f32_e32 v115, v67, v115
	v_exp_f32_e32 v71, v71
	s_waitcnt lgkmcnt(0)
	v_mfma_f32_32x32x16_bf16 v[32:47], v[176:179], v[180:183], v[32:47]
	ds_read_b64_tr_b16 v[180:181], v158 offset:0x400
	ds_read_b64_tr_b16 v[182:183], v158 offset:0xc00
	v_fmamk_f32 v72, v72, 0x3e0293ee, v114
	v_add_f32_e32 v115, v68, v115
	v_exp_f32_e32 v72, v72
	v_fmamk_f32 v73, v73, 0x3e0293ee, v114
	v_max3_f32 v112, v112, v74, v75
	v_add_f32_e32 v115, v69, v115
	v_exp_f32_e32 v73, v73
	v_mfma_f32_32x32x16_bf16 v[32:47], v[124:127], v[184:187], v[32:47]
	ds_read_b64_tr_b16 v[184:185], v158 offset:0x1400
	ds_read_b64_tr_b16 v[186:187], v158 offset:0x1c00
	v_fmamk_f32 v74, v74, 0x3e0293ee, v114
	v_add_f32_e32 v115, v70, v115
	v_exp_f32_e32 v74, v74
	v_fmamk_f32 v75, v75, 0x3e0293ee, v114
	v_max3_f32 v112, v112, v76, v77
	v_add_f32_e32 v115, v71, v115
	v_exp_f32_e32 v75, v75
	v_mfma_f32_32x32x16_bf16 v[32:47], v[172:175], v[188:191], v[32:47]
	ds_read_b64_tr_b16 v[188:189], v158 offset:0x2400
	ds_read_b64_tr_b16 v[190:191], v158 offset:0x2c00
	v_fmamk_f32 v76, v76, 0x3e0293ee, v114
	v_add_f32_e32 v115, v72, v115
	v_exp_f32_e32 v76, v76
	v_fmamk_f32 v77, v77, 0x3e0293ee, v114
	v_max3_f32 v112, v112, v78, v79
	v_add_f32_e32 v115, v73, v115
	v_exp_f32_e32 v77, v77
	v_mfma_f32_32x32x16_bf16 v[32:47], v[168:171], v[192:195], v[32:47]
	ds_read_b64_tr_b16 v[192:193], v158 offset:0x3400
	ds_read_b64_tr_b16 v[194:195], v158 offset:0x3c00
	v_fmamk_f32 v78, v78, 0x3e0293ee, v114
	v_add_f32_e32 v115, v74, v115
	v_exp_f32_e32 v78, v78
	v_fmac_f32_e32 v114, 0x3e0293ee, v79
	v_add_f32_e32 v115, v75, v115
	v_exp_f32_e32 v79, v114
	v_add_f32_e32 v114, v76, v115
	s_waitcnt lgkmcnt(0)
	v_mfma_f32_32x32x16_bf16 v[16:31], v[176:179], v[180:183], v[16:31]
	ds_read_b64_tr_b16 v[180:181], v158 offset:0x600
	ds_read_b64_tr_b16 v[182:183], v158 offset:0xe00
	v_mov_b32_e32 v113, v112
	v_add_f32_e32 v114, v77, v114
	s_nop 0
	v_permlane32_swap_b32_e32 v112, v113
	v_add_f32_e32 v114, v78, v114
	v_add_f32_e32 v120, v79, v114
	v_max_f32_e32 v113, v113, v113
	v_max_f32_e32 v112, v112, v112
	v_mfma_f32_32x32x16_bf16 v[16:31], v[124:127], v[184:187], v[16:31]
	ds_read_b64_tr_b16 v[184:185], v158 offset:0x1600
	ds_read_b64_tr_b16 v[186:187], v158 offset:0x1e00
	v_max_f32_e32 v164, v112, v113
	v_mov_b32_e32 v121, v120
	v_cvt_pk_bf16_f32 v112, v64, v65
	v_cvt_pk_bf16_f32 v113, v66, v67
	v_cvt_pk_bf16_f32 v114, v68, v69
	v_cvt_pk_bf16_f32 v115, v70, v71
	v_cvt_pk_bf16_f32 v116, v72, v73
	v_mfma_f32_32x32x16_bf16 v[16:31], v[172:175], v[188:191], v[16:31]
	ds_read_b64_tr_b16 v[188:189], v158 offset:0x2600
	ds_read_b64_tr_b16 v[190:191], v158 offset:0x2e00
	v_cvt_pk_bf16_f32 v117, v74, v75
	v_cvt_pk_bf16_f32 v118, v76, v77
	v_cvt_pk_bf16_f32 v119, v78, v79
	s_nop 1
	v_permlane32_swap_b32_e32 v120, v121
	v_permlane32_swap_b32_e32 v112, v114
	v_permlane32_swap_b32_e32 v113, v115
	v_permlane32_swap_b32_e32 v116, v118
	v_mfma_f32_32x32x16_bf16 v[16:31], v[168:171], v[192:195], v[16:31]
	ds_read_b64_tr_b16 v[192:193], v158 offset:0x3600
	ds_read_b64_tr_b16 v[194:195], v158 offset:0x3e00
	v_permlane32_swap_b32_e32 v117, v119
	ds_write_b128 v157, v[112:115] offset:4096
	ds_write_b128 v157, v[116:119] offset:5120
	ds_write_b32 v160, v164 offset:8448
	v_add_f32_e32 v120, v120, v121
	v_add_f32_e32 v155, v155, v120
	s_waitcnt lgkmcnt(0)
	v_mfma_f32_32x32x16_bf16 v[0:15], v[176:179], v[180:183], v[0:15]
	v_mfma_f32_32x32x16_bf16 v[0:15], v[124:127], v[184:187], v[0:15]
	v_mfma_f32_32x32x16_bf16 v[0:15], v[172:175], v[188:191], v[0:15]
	v_mfma_f32_32x32x16_bf16 v[0:15], v[168:171], v[192:195], v[0:15]
	s_waitcnt vmcnt(0)
	s_waitcnt vmcnt(0) lgkmcnt(0)
	s_barrier
	s_branch .LBB0_748

.Li1_sm:
	ds_read_b64_tr_b16 v[188:189], v158 offset:0xa000
	ds_read_b64_tr_b16 v[190:191], v158 offset:0xa800
	ds_read_b64_tr_b16 v[192:193], v158 offset:0xb000
	ds_read_b64_tr_b16 v[194:195], v158 offset:0xb800
	s_waitcnt lgkmcnt(4)
	s_nop 1
	v_mfma_f32_32x32x16_bf16 v[48:63], v[176:179], v[180:183], v[48:63]
	ds_read_b64_tr_b16 v[180:181], v158 offset:0x8200
	ds_read_b64_tr_b16 v[182:183], v158 offset:0x8a00
	v_mul_f32_e32 v114, 0xbe0293ee, v165
	v_max_f32_e32 v112, v65, v65
	v_max_f32_e32 v113, v64, v64
	v_fmamk_f32 v64, v64, 0x3e0293ee, v114
	v_max_f32_e32 v112, v113, v112
	v_exp_f32_e32 v64, v64
	v_fmamk_f32 v65, v65, 0x3e0293ee, v114
	v_mfma_f32_32x32x16_bf16 v[48:63], v[168:171], v[184:187], v[48:63]
	ds_read_b64_tr_b16 v[184:185], v158 offset:0x9200
	ds_read_b64_tr_b16 v[186:187], v158 offset:0x9a00
	v_max3_f32 v112, v112, v66, v67
	v_exp_f32_e32 v65, v65
	v_fmamk_f32 v66, v66, 0x3e0293ee, v114
	v_exp_f32_e32 v66, v66
	v_fmamk_f32 v67, v67, 0x3e0293ee, v114
	v_max3_f32 v112, v112, v68, v69
	v_exp_f32_e32 v67, v67
	s_waitcnt lgkmcnt(6)
	v_mfma_f32_32x32x16_bf16 v[48:63], v[172:175], v[188:191], v[48:63]
	ds_read_b64_tr_b16 v[188:189], v158 offset:0xa200
	ds_read_b64_tr_b16 v[190:191], v158 offset:0xaa00
	v_fmamk_f32 v68, v68, 0x3e0293ee, v114
	v_add_f32_e32 v115, 0, v64
	v_exp_f32_e32 v68, v68
	v_fmamk_f32 v69, v69, 0x3e0293ee, v114
	v_max3_f32 v112, v112, v70, v71
	v_add_f32_e32 v115, v65, v115
	v_exp_f32_e32 v69, v69
	s_waitcnt lgkmcnt(6)
	v_mfma_f32_32x32x16_bf16 v[48:63], v[124:127], v[192:195], v[48:63]
	ds_read_b64_tr_b16 v[192:193], v158 offset:0xb200
	ds_read_b64_tr_b16 v[194:195], v158 offset:0xba00
	v_fmamk_f32 v70, v70, 0x3e0293ee, v114
	v_add_f32_e32 v115, v66, v115
	v_exp_f32_e32 v70, v70
	v_fmamk_f32 v71, v71, 0x3e0293ee, v114
	v_max3_f32 v112, v112, v72, v73
	v_add_f32_e32 v115, v67, v115
	v_exp_f32_e32 v71, v71
	s_waitcnt lgkmcnt(0)
	v_mfma_f32_32x32x16_bf16 v[32:47], v[176:179], v[180:183], v[32:47]
	ds_read_b64_tr_b16 v[180:181], v158 offset:0x8400
	ds_read_b64_tr_b16 v[182:183], v158 offset:0x8c00
	v_fmamk_f32 v72, v72, 0x3e0293ee, v114
	v_add_f32_e32 v115, v68, v115
	v_exp_f32_e32 v72, v72
	v_fmamk_f32 v73, v73, 0x3e0293ee, v114
	v_max3_f32 v112, v112, v74, v75
	v_add_f32_e32 v115, v69, v115
	v_exp_f32_e32 v73, v73
	v_mfma_f32_32x32x16_bf16 v[32:47], v[168:171], v[184:187], v[32:47]
	ds_read_b64_tr_b16 v[184:185], v158 offset:0x9400
	ds_read_b64_tr_b16 v[186:187], v158 offset:0x9c00
	v_fmamk_f32 v74, v74, 0x3e0293ee, v114
	v_add_f32_e32 v115, v70, v115
	v_exp_f32_e32 v74, v74
	v_fmamk_f32 v75, v75, 0x3e0293ee, v114
	v_max3_f32 v112, v112, v76, v77
	v_add_f32_e32 v115, v71, v115
	v_exp_f32_e32 v75, v75
	v_mfma_f32_32x32x16_bf16 v[32:47], v[172:175], v[188:191], v[32:47]
	ds_read_b64_tr_b16 v[188:189], v158 offset:0xa400
	ds_read_b64_tr_b16 v[190:191], v158 offset:0xac00
	v_fmamk_f32 v76, v76, 0x3e0293ee, v114
	v_add_f32_e32 v115, v72, v115
	v_exp_f32_e32 v76, v76
	v_fmamk_f32 v77, v77, 0x3e0293ee, v114
	v_max3_f32 v112, v112, v78, v79
	v_add_f32_e32 v115, v73, v115
	v_exp_f32_e32 v77, v77
	v_mfma_f32_32x32x16_bf16 v[32:47], v[124:127], v[192:195], v[32:47]
	ds_read_b64_tr_b16 v[192:193], v158 offset:0xb400
	ds_read_b64_tr_b16 v[194:195], v158 offset:0xbc00
	v_fmamk_f32 v78, v78, 0x3e0293ee, v114
	v_add_f32_e32 v115, v74, v115
	v_exp_f32_e32 v78, v78
	v_fmac_f32_e32 v114, 0x3e0293ee, v79
	v_add_f32_e32 v115, v75, v115
	v_exp_f32_e32 v79, v114
	v_add_f32_e32 v114, v76, v115
	s_waitcnt lgkmcnt(0)
	v_mfma_f32_32x32x16_bf16 v[16:31], v[176:179], v[180:183], v[16:31]
	ds_read_b64_tr_b16 v[180:181], v158 offset:0x8600
	ds_read_b64_tr_b16 v[182:183], v158 offset:0x8e00
	v_mov_b32_e32 v113, v112
	v_add_f32_e32 v114, v77, v114
	s_nop 0
	v_permlane32_swap_b32_e32 v112, v113
	v_add_f32_e32 v114, v78, v114
	v_add_f32_e32 v120, v79, v114
	v_max_f32_e32 v113, v113, v113
	v_max_f32_e32 v112, v112, v112
	v_mfma_f32_32x32x16_bf16 v[16:31], v[168:171], v[184:187], v[16:31]
	ds_read_b64_tr_b16 v[184:185], v158 offset:0x9600
	ds_read_b64_tr_b16 v[186:187], v158 offset:0x9e00
	v_max_f32_e32 v164, v112, v113
	v_mov_b32_e32 v121, v120
	v_cvt_pk_bf16_f32 v112, v64, v65
	v_cvt_pk_bf16_f32 v113, v66, v67
	v_cvt_pk_bf16_f32 v114, v68, v69
	v_cvt_pk_bf16_f32 v115, v70, v71
	v_cvt_pk_bf16_f32 v116, v72, v73
	v_mfma_f32_32x32x16_bf16 v[16:31], v[172:175], v[188:191], v[16:31]
	ds_read_b64_tr_b16 v[188:189], v158 offset:0xa600
	ds_read_b64_tr_b16 v[190:191], v158 offset:0xae00
	v_cvt_pk_bf16_f32 v117, v74, v75
	v_cvt_pk_bf16_f32 v118, v76, v77
	v_cvt_pk_bf16_f32 v119, v78, v79
	s_nop 1
	v_permlane32_swap_b32_e32 v120, v121
	v_permlane32_swap_b32_e32 v112, v114
	v_permlane32_swap_b32_e32 v113, v115
	v_permlane32_swap_b32_e32 v116, v118
	v_mfma_f32_32x32x16_bf16 v[16:31], v[124:127], v[192:195], v[16:31]
	ds_read_b64_tr_b16 v[192:193], v158 offset:0xb600
	ds_read_b64_tr_b16 v[194:195], v158 offset:0xbe00
	v_permlane32_swap_b32_e32 v117, v119
	ds_write_b128 v157, v[112:115]
	ds_write_b128 v157, v[116:119] offset:1024
	ds_write_b32 v160, v164 offset:8192
	v_add_f32_e32 v120, v120, v121
	v_add_f32_e32 v155, v155, v120
	s_waitcnt lgkmcnt(0)
	v_mfma_f32_32x32x16_bf16 v[0:15], v[176:179], v[180:183], v[0:15]
	v_mfma_f32_32x32x16_bf16 v[0:15], v[168:171], v[184:187], v[0:15]
	v_mfma_f32_32x32x16_bf16 v[0:15], v[172:175], v[188:191], v[0:15]
	v_mfma_f32_32x32x16_bf16 v[0:15], v[124:127], v[192:195], v[0:15]
	s_waitcnt vmcnt(0)
	s_waitcnt vmcnt(0) lgkmcnt(0)
	s_barrier
	s_branch .LBB0_733

.LBB0_762:
	s_xor_b64 s[50:51], s[48:49], -1
	s_waitcnt vmcnt(0)
	s_barrier
	s_and_saveexec_b64 s[48:49], s[4:5]
	v_lshl_add_u32 v64, v143, 2, s80
	ds_write_b32 v64, v155 offset:8704
	s_or_b64 exec, exec, s[48:49]
	v_lshl_add_u32 v68, v146, 2, s66
	s_waitcnt lgkmcnt(0)
	s_barrier
	ds_read_b128 v[88:91], v68 offset:8704
	ds_read_b128 v[92:95], v68 offset:8832
	s_lshl_b64 s[4:5], s[46:47], 19
	ds_read_b128 v[80:83], v68 offset:8736
	ds_read_b128 v[84:87], v68 offset:8864
	s_add_u32 s6, s94, s4
	s_addc_u32 s7, s95, s5
	s_waitcnt lgkmcnt(2)
	v_add_f32_e32 v64, v88, v92
	v_rcp_f32_e32 v88, v64
	ds_read_b128 v[72:75], v68 offset:8768
	ds_read_b128 v[64:67], v68 offset:8800
	ds_read_b128 v[76:79], v68 offset:8896
	ds_read_b128 v[68:71], v68 offset:8928
	v_and_b32_e32 v92, 1, v144
	v_cmp_eq_u32_e64 s[4:5], 0, v92
	v_mul_f32_e32 v48, v48, v88
	s_nop 1
	v_mov_b32_dpp v92, v48 quad_perm:[1,0,3,2] row_mask:0xf bank_mask:0xf
	s_nop 0
	v_lshlrev_b32_e32 v128, 1, v143
	v_lshl_add_u64 v[96:97], s[6:7], 0, v[128:129]
	v_lshlrev_b32_e32 v128, 14, v142
	v_lshl_add_u64 v[96:97], v[96:97], 0, v[128:129]
	s_and_saveexec_b64 s[46:47], s[4:5]
	s_cbranch_execz .LBB0_766
	s_waitcnt lgkmcnt(0)
	v_cvt_pk_bf16_f32 v48, v48, v92
	global_store_dword v[96:97], v48, off
.LBB0_766:
	s_or_b64 exec, exec, s[46:47]
	v_mul_f32_e32 v32, v32, v88
	s_nop 1
	v_mov_b32_dpp v48, v32 quad_perm:[1,0,3,2] row_mask:0xf bank_mask:0xf
	s_nop 0
	s_and_saveexec_b64 s[46:47], s[4:5]
	s_cbranch_execz .LBB0_768
	s_waitcnt lgkmcnt(0)
	v_cvt_pk_bf16_f32 v32, v32, v48
	global_store_dword v[96:97], v32, off offset:64
.LBB0_768:
	s_or_b64 exec, exec, s[46:47]
	v_mul_f32_e32 v16, v16, v88
	s_nop 1
	v_mov_b32_dpp v32, v16 quad_perm:[1,0,3,2] row_mask:0xf bank_mask:0xf
	s_nop 0
	s_and_saveexec_b64 s[46:47], s[4:5]
	s_cbranch_execz .LBB0_770
	s_waitcnt lgkmcnt(0)
	v_cvt_pk_bf16_f32 v16, v16, v32
	global_store_dword v[96:97], v16, off offset:128
.LBB0_770:
	s_or_b64 exec, exec, s[46:47]
	v_mul_f32_e32 v0, v0, v88
	s_nop 1
	v_mov_b32_dpp v16, v0 quad_perm:[1,0,3,2] row_mask:0xf bank_mask:0xf
	s_nop 0
	s_and_saveexec_b64 s[46:47], s[4:5]
	s_cbranch_execz .LBB0_772
	s_waitcnt lgkmcnt(0)
	v_cvt_pk_bf16_f32 v0, v0, v16
	global_store_dword v[96:97], v0, off offset:192
.LBB0_772:
	s_or_b64 exec, exec, s[46:47]
	v_add_f32_e32 v0, v89, v93
	v_rcp_f32_e32 v0, v0
	s_waitcnt lgkmcnt(0)
	v_mul_f32_e32 v16, v49, v0
	s_nop 1
	v_mov_b32_dpp v32, v16 quad_perm:[1,0,3,2] row_mask:0xf bank_mask:0xf
	s_nop 0
	s_and_saveexec_b64 s[46:47], s[4:5]
	s_cbranch_execz .LBB0_774
	v_add_co_u32_e32 v48, vcc, 0x1000, v96
	s_waitcnt lgkmcnt(0)
	v_cvt_pk_bf16_f32 v16, v16, v32
	s_nop 0
	v_addc_co_u32_e32 v49, vcc, 0, v97, vcc
	global_store_dword v[48:49], v16, off
.LBB0_774:
	s_or_b64 exec, exec, s[46:47]
	v_mul_f32_e32 v16, v33, v0
	s_waitcnt lgkmcnt(0)
	s_nop 1
	v_mov_b32_dpp v32, v16 quad_perm:[1,0,3,2] row_mask:0xf bank_mask:0xf
	s_nop 0
	s_and_saveexec_b64 s[46:47], s[4:5]
	s_cbranch_execz .LBB0_776
	s_waitcnt lgkmcnt(0)
	v_cvt_pk_bf16_f32 v16, v16, v32
	v_add_co_u32_e32 v32, vcc, 0x1000, v96
	s_nop 1
	v_addc_co_u32_e32 v33, vcc, 0, v97, vcc
	global_store_dword v[32:33], v16, off offset:64
.LBB0_776:
	s_or_b64 exec, exec, s[46:47]
	v_mul_f32_e32 v16, v17, v0
	s_nop 1
	v_mov_b32_dpp v17, v16 quad_perm:[1,0,3,2] row_mask:0xf bank_mask:0xf
	s_nop 0
	s_and_saveexec_b64 s[46:47], s[4:5]
	s_cbranch_execz .LBB0_778
	s_waitcnt lgkmcnt(0)
	v_cvt_pk_bf16_f32 v32, v16, v17
	v_add_co_u32_e32 v16, vcc, 0x1000, v96
	s_nop 1
	v_addc_co_u32_e32 v17, vcc, 0, v97, vcc
	global_store_dword v[16:17], v32, off offset:128
.LBB0_778:
	s_or_b64 exec, exec, s[46:47]
	v_mul_f32_e32 v0, v1, v0
	s_nop 1
	v_mov_b32_dpp v1, v0 quad_perm:[1,0,3,2] row_mask:0xf bank_mask:0xf
	s_nop 0
	s_and_saveexec_b64 s[46:47], s[4:5]
	s_cbranch_execz .LBB0_780
	s_waitcnt lgkmcnt(0)
	v_cvt_pk_bf16_f32 v16, v0, v1
	v_add_co_u32_e32 v0, vcc, 0x1000, v96
	s_nop 1
	v_addc_co_u32_e32 v1, vcc, 0, v97, vcc
	global_store_dword v[0:1], v16, off offset:192
.LBB0_780:
	s_or_b64 exec, exec, s[46:47]
	v_add_f32_e32 v0, v90, v94
	v_rcp_f32_e32 v0, v0
	s_waitcnt lgkmcnt(0)
	v_mul_f32_e32 v1, v50, v0
	s_nop 1
	v_mov_b32_dpp v16, v1 quad_perm:[1,0,3,2] row_mask:0xf bank_mask:0xf
	s_nop 0
	s_and_saveexec_b64 s[46:47], s[4:5]
	s_cbranch_execz .LBB0_782
	s_waitcnt lgkmcnt(0)
	v_cvt_pk_bf16_f32 v1, v1, v16
	v_add_co_u32_e32 v16, vcc, 0x2000, v96
	s_nop 1
	v_addc_co_u32_e32 v17, vcc, 0, v97, vcc
	global_store_dword v[16:17], v1, off
.LBB0_782:
	s_or_b64 exec, exec, s[46:47]
	v_mul_f32_e32 v1, v34, v0
	s_waitcnt lgkmcnt(0)
	s_nop 1
	v_mov_b32_dpp v16, v1 quad_perm:[1,0,3,2] row_mask:0xf bank_mask:0xf
	s_nop 0
	s_and_saveexec_b64 s[46:47], s[4:5]
	s_cbranch_execz .LBB0_784
	s_waitcnt lgkmcnt(0)
	v_cvt_pk_bf16_f32 v1, v1, v16
	v_add_co_u32_e32 v16, vcc, 0x2000, v96
	s_nop 1
	v_addc_co_u32_e32 v17, vcc, 0, v97, vcc
	global_store_dword v[16:17], v1, off offset:64
.LBB0_784:
	s_or_b64 exec, exec, s[46:47]
	v_mul_f32_e32 v1, v18, v0
	s_waitcnt lgkmcnt(0)
	s_nop 1
	v_mov_b32_dpp v16, v1 quad_perm:[1,0,3,2] row_mask:0xf bank_mask:0xf
	s_nop 0
	s_and_saveexec_b64 s[46:47], s[4:5]
	s_cbranch_execz .LBB0_786
	s_waitcnt lgkmcnt(0)
	v_cvt_pk_bf16_f32 v1, v1, v16
	v_add_co_u32_e32 v16, vcc, 0x2000, v96
	s_nop 1
	v_addc_co_u32_e32 v17, vcc, 0, v97, vcc
	global_store_dword v[16:17], v1, off offset:128
.LBB0_786:
	s_or_b64 exec, exec, s[46:47]
	v_mul_f32_e32 v0, v2, v0
	s_nop 1
	v_mov_b32_dpp v1, v0 quad_perm:[1,0,3,2] row_mask:0xf bank_mask:0xf
	s_nop 0
	s_and_saveexec_b64 s[46:47], s[4:5]
	s_cbranch_execz .LBB0_788
	s_waitcnt lgkmcnt(0)
	v_cvt_pk_bf16_f32 v2, v0, v1
	v_add_co_u32_e32 v0, vcc, 0x2000, v96
	s_nop 1
	v_addc_co_u32_e32 v1, vcc, 0, v97, vcc
	global_store_dword v[0:1], v2, off offset:192
.LBB0_788:
	s_or_b64 exec, exec, s[46:47]
	v_add_f32_e32 v0, v91, v95
	v_rcp_f32_e32 v0, v0
	s_waitcnt lgkmcnt(0)
	v_mul_f32_e32 v1, v51, v0
	s_nop 1
	v_mov_b32_dpp v2, v1 quad_perm:[1,0,3,2] row_mask:0xf bank_mask:0xf
	s_nop 0
	s_and_saveexec_b64 s[46:47], s[4:5]
	s_cbranch_execz .LBB0_790
	v_add_co_u32_e32 v16, vcc, 0x3000, v96
	s_waitcnt lgkmcnt(0)
	v_cvt_pk_bf16_f32 v1, v1, v2
	s_nop 0
	v_addc_co_u32_e32 v17, vcc, 0, v97, vcc
	global_store_dword v[16:17], v1, off
.LBB0_790:
	s_or_b64 exec, exec, s[46:47]
	v_mul_f32_e32 v1, v35, v0
	s_waitcnt lgkmcnt(0)
	s_nop 1
	v_mov_b32_dpp v2, v1 quad_perm:[1,0,3,2] row_mask:0xf bank_mask:0xf
	s_nop 0
	s_and_saveexec_b64 s[46:47], s[4:5]
	s_cbranch_execz .LBB0_792
	v_add_co_u32_e32 v16, vcc, 0x3000, v96
	s_waitcnt lgkmcnt(0)
	v_cvt_pk_bf16_f32 v1, v1, v2
	s_nop 0
	v_addc_co_u32_e32 v17, vcc, 0, v97, vcc
	global_store_dword v[16:17], v1, off offset:64
.LBB0_792:
	s_or_b64 exec, exec, s[46:47]
	v_mul_f32_e32 v1, v19, v0
	s_waitcnt lgkmcnt(0)
	s_nop 1
	v_mov_b32_dpp v2, v1 quad_perm:[1,0,3,2] row_mask:0xf bank_mask:0xf
	s_nop 0
	s_and_saveexec_b64 s[46:47], s[4:5]
	s_cbranch_execz .LBB0_794
	v_add_co_u32_e32 v16, vcc, 0x3000, v96
	s_waitcnt lgkmcnt(0)
	v_cvt_pk_bf16_f32 v1, v1, v2
	s_nop 0
	v_addc_co_u32_e32 v17, vcc, 0, v97, vcc
	global_store_dword v[16:17], v1, off offset:128
.LBB0_794:
	s_or_b64 exec, exec, s[46:47]
	v_mul_f32_e32 v0, v3, v0
	s_nop 1
	v_mov_b32_dpp v1, v0 quad_perm:[1,0,3,2] row_mask:0xf bank_mask:0xf
	s_nop 0
	s_and_saveexec_b64 s[46:47], s[4:5]
	s_cbranch_execz .LBB0_796
	s_waitcnt lgkmcnt(0)
	v_cvt_pk_bf16_f32 v2, v0, v1
	v_add_co_u32_e32 v0, vcc, 0x3000, v96
	s_nop 1
	v_addc_co_u32_e32 v1, vcc, 0, v97, vcc
	global_store_dword v[0:1], v2, off offset:192
.LBB0_796:
	s_or_b64 exec, exec, s[46:47]
	v_add_f32_e32 v0, v80, v84
	v_rcp_f32_e32 v0, v0
	s_waitcnt lgkmcnt(0)
	v_mul_f32_e32 v1, v52, v0
	s_nop 1
	v_mov_b32_dpp v2, v1 quad_perm:[1,0,3,2] row_mask:0xf bank_mask:0xf
	s_nop 0
	s_and_saveexec_b64 s[46:47], s[4:5]
	s_cbranch_execz .LBB0_798
	s_waitcnt lgkmcnt(0)
	v_cvt_pk_bf16_f32 v1, v1, v2
	v_add_co_u32_e32 v2, vcc, 0x8000, v96
	s_nop 1
	v_addc_co_u32_e32 v3, vcc, 0, v97, vcc
	global_store_dword v[2:3], v1, off
.LBB0_798:
	s_or_b64 exec, exec, s[46:47]
	v_mul_f32_e32 v1, v36, v0
	s_waitcnt lgkmcnt(0)
	s_nop 1
	v_mov_b32_dpp v2, v1 quad_perm:[1,0,3,2] row_mask:0xf bank_mask:0xf
	s_nop 0
	s_and_saveexec_b64 s[46:47], s[4:5]
	s_cbranch_execz .LBB0_800
	s_waitcnt lgkmcnt(0)
	v_cvt_pk_bf16_f32 v1, v1, v2
	v_add_co_u32_e32 v2, vcc, 0x8000, v96
	s_nop 1
	v_addc_co_u32_e32 v3, vcc, 0, v97, vcc
	global_store_dword v[2:3], v1, off offset:64
.LBB0_800:
	s_or_b64 exec, exec, s[46:47]
	v_mul_f32_e32 v1, v20, v0
	s_waitcnt lgkmcnt(0)
	s_nop 1
	v_mov_b32_dpp v2, v1 quad_perm:[1,0,3,2] row_mask:0xf bank_mask:0xf
	s_nop 0
	s_and_saveexec_b64 s[46:47], s[4:5]
	s_cbranch_execz .LBB0_802
	s_waitcnt lgkmcnt(0)
	v_cvt_pk_bf16_f32 v1, v1, v2
	v_add_co_u32_e32 v2, vcc, 0x8000, v96
	s_nop 1
	v_addc_co_u32_e32 v3, vcc, 0, v97, vcc
	global_store_dword v[2:3], v1, off offset:128
.LBB0_802:
	s_or_b64 exec, exec, s[46:47]
	v_mul_f32_e32 v0, v4, v0
	s_nop 1
	v_mov_b32_dpp v1, v0 quad_perm:[1,0,3,2] row_mask:0xf bank_mask:0xf
	s_nop 0
	s_and_saveexec_b64 s[46:47], s[4:5]
	s_cbranch_execz .LBB0_804
	s_waitcnt lgkmcnt(0)
	v_cvt_pk_bf16_f32 v2, v0, v1
	v_add_co_u32_e32 v0, vcc, 0x8000, v96
	s_nop 1
	v_addc_co_u32_e32 v1, vcc, 0, v97, vcc
	global_store_dword v[0:1], v2, off offset:192
.LBB0_804:
	s_or_b64 exec, exec, s[46:47]
	v_add_f32_e32 v0, v81, v85
	v_rcp_f32_e32 v0, v0
	s_waitcnt lgkmcnt(0)
	v_mul_f32_e32 v1, v53, v0
	s_nop 1
	v_mov_b32_dpp v2, v1 quad_perm:[1,0,3,2] row_mask:0xf bank_mask:0xf
	s_nop 0
	s_and_saveexec_b64 s[46:47], s[4:5]
	s_cbranch_execz .LBB0_806
	s_waitcnt lgkmcnt(0)
	v_cvt_pk_bf16_f32 v1, v1, v2
	v_add_co_u32_e32 v2, vcc, 0x9000, v96
	s_nop 1
	v_addc_co_u32_e32 v3, vcc, 0, v97, vcc
	global_store_dword v[2:3], v1, off
.LBB0_806:
	s_or_b64 exec, exec, s[46:47]
	v_mul_f32_e32 v1, v37, v0
	s_waitcnt lgkmcnt(0)
	s_nop 1
	v_mov_b32_dpp v2, v1 quad_perm:[1,0,3,2] row_mask:0xf bank_mask:0xf
	s_nop 0
	s_and_saveexec_b64 s[46:47], s[4:5]
	s_cbranch_execz .LBB0_808
	s_waitcnt lgkmcnt(0)
	v_cvt_pk_bf16_f32 v1, v1, v2
	v_add_co_u32_e32 v2, vcc, 0x9000, v96
	s_nop 1
	v_addc_co_u32_e32 v3, vcc, 0, v97, vcc
	global_store_dword v[2:3], v1, off offset:64
.LBB0_808:
	s_or_b64 exec, exec, s[46:47]
	v_mul_f32_e32 v1, v21, v0
	s_waitcnt lgkmcnt(0)
	s_nop 1
	v_mov_b32_dpp v2, v1 quad_perm:[1,0,3,2] row_mask:0xf bank_mask:0xf
	s_nop 0
	s_and_saveexec_b64 s[46:47], s[4:5]
	s_cbranch_execz .LBB0_810
	s_waitcnt lgkmcnt(0)
	v_cvt_pk_bf16_f32 v1, v1, v2
	v_add_co_u32_e32 v2, vcc, 0x9000, v96
	s_nop 1
	v_addc_co_u32_e32 v3, vcc, 0, v97, vcc
	global_store_dword v[2:3], v1, off offset:128
.LBB0_810:
	s_or_b64 exec, exec, s[46:47]
	v_mul_f32_e32 v0, v5, v0
	s_nop 1
	v_mov_b32_dpp v1, v0 quad_perm:[1,0,3,2] row_mask:0xf bank_mask:0xf
	s_nop 0
	s_and_saveexec_b64 s[46:47], s[4:5]
	s_cbranch_execz .LBB0_812
	s_waitcnt lgkmcnt(0)
	v_cvt_pk_bf16_f32 v2, v0, v1
	v_add_co_u32_e32 v0, vcc, 0x9000, v96
	s_nop 1
	v_addc_co_u32_e32 v1, vcc, 0, v97, vcc
	global_store_dword v[0:1], v2, off offset:192
.LBB0_812:
	s_or_b64 exec, exec, s[46:47]
	v_add_f32_e32 v0, v82, v86
	v_rcp_f32_e32 v0, v0
	s_waitcnt lgkmcnt(0)
	v_mul_f32_e32 v1, v54, v0
	s_nop 1
	v_mov_b32_dpp v2, v1 quad_perm:[1,0,3,2] row_mask:0xf bank_mask:0xf
	s_nop 0
	s_and_saveexec_b64 s[46:47], s[4:5]
	s_cbranch_execz .LBB0_814
	s_waitcnt lgkmcnt(0)
	v_cvt_pk_bf16_f32 v1, v1, v2
	v_add_co_u32_e32 v2, vcc, 0xa000, v96
	s_nop 1
	v_addc_co_u32_e32 v3, vcc, 0, v97, vcc
	global_store_dword v[2:3], v1, off
.LBB0_814:
	s_or_b64 exec, exec, s[46:47]
	v_mul_f32_e32 v1, v38, v0
	s_waitcnt lgkmcnt(0)
	s_nop 1
	v_mov_b32_dpp v2, v1 quad_perm:[1,0,3,2] row_mask:0xf bank_mask:0xf
	s_nop 0
	s_and_saveexec_b64 s[46:47], s[4:5]
	s_cbranch_execz .LBB0_816
	s_waitcnt lgkmcnt(0)
	v_cvt_pk_bf16_f32 v1, v1, v2
	v_add_co_u32_e32 v2, vcc, 0xa000, v96
	s_nop 1
	v_addc_co_u32_e32 v3, vcc, 0, v97, vcc
	global_store_dword v[2:3], v1, off offset:64
.LBB0_816:
	s_or_b64 exec, exec, s[46:47]
	v_mul_f32_e32 v1, v22, v0
	s_waitcnt lgkmcnt(0)
	s_nop 1
	v_mov_b32_dpp v2, v1 quad_perm:[1,0,3,2] row_mask:0xf bank_mask:0xf
	s_nop 0
	s_and_saveexec_b64 s[46:47], s[4:5]
	s_cbranch_execz .LBB0_818
	s_waitcnt lgkmcnt(0)
	v_cvt_pk_bf16_f32 v1, v1, v2
	v_add_co_u32_e32 v2, vcc, 0xa000, v96
	s_nop 1
	v_addc_co_u32_e32 v3, vcc, 0, v97, vcc
	global_store_dword v[2:3], v1, off offset:128
.LBB0_818:
	s_or_b64 exec, exec, s[46:47]
	v_mul_f32_e32 v0, v6, v0
	s_nop 1
	v_mov_b32_dpp v1, v0 quad_perm:[1,0,3,2] row_mask:0xf bank_mask:0xf
	s_nop 0
	s_and_saveexec_b64 s[46:47], s[4:5]
	s_cbranch_execz .LBB0_820
	s_waitcnt lgkmcnt(0)
	v_cvt_pk_bf16_f32 v2, v0, v1
	v_add_co_u32_e32 v0, vcc, 0xa000, v96
	s_nop 1
	v_addc_co_u32_e32 v1, vcc, 0, v97, vcc
	global_store_dword v[0:1], v2, off offset:192
.LBB0_820:
	s_or_b64 exec, exec, s[46:47]
	v_add_f32_e32 v0, v83, v87
	v_rcp_f32_e32 v0, v0
	s_waitcnt lgkmcnt(0)
	v_mul_f32_e32 v1, v55, v0
	s_nop 1
	v_mov_b32_dpp v2, v1 quad_perm:[1,0,3,2] row_mask:0xf bank_mask:0xf
	s_nop 0
	s_and_saveexec_b64 s[46:47], s[4:5]
	s_cbranch_execz .LBB0_822
	s_waitcnt lgkmcnt(0)
	v_cvt_pk_bf16_f32 v1, v1, v2
	v_add_co_u32_e32 v2, vcc, 0xb000, v96
	s_nop 1
	v_addc_co_u32_e32 v3, vcc, 0, v97, vcc
	global_store_dword v[2:3], v1, off
.LBB0_822:
	s_or_b64 exec, exec, s[46:47]
	v_mul_f32_e32 v1, v39, v0
	s_waitcnt lgkmcnt(0)
	s_nop 1
	v_mov_b32_dpp v2, v1 quad_perm:[1,0,3,2] row_mask:0xf bank_mask:0xf
	s_nop 0
	s_and_saveexec_b64 s[46:47], s[4:5]
	s_cbranch_execz .LBB0_824
	s_waitcnt lgkmcnt(0)
	v_cvt_pk_bf16_f32 v1, v1, v2
	v_add_co_u32_e32 v2, vcc, 0xb000, v96
	s_nop 1
	v_addc_co_u32_e32 v3, vcc, 0, v97, vcc
	global_store_dword v[2:3], v1, off offset:64
.LBB0_824:
	s_or_b64 exec, exec, s[46:47]
	v_mul_f32_e32 v1, v23, v0
	s_waitcnt lgkmcnt(0)
	s_nop 1
	v_mov_b32_dpp v2, v1 quad_perm:[1,0,3,2] row_mask:0xf bank_mask:0xf
	s_nop 0
	s_and_saveexec_b64 s[46:47], s[4:5]
	s_cbranch_execz .LBB0_826
	s_waitcnt lgkmcnt(0)
	v_cvt_pk_bf16_f32 v1, v1, v2
	v_add_co_u32_e32 v2, vcc, 0xb000, v96
	s_nop 1
	v_addc_co_u32_e32 v3, vcc, 0, v97, vcc
	global_store_dword v[2:3], v1, off offset:128
.LBB0_826:
	s_or_b64 exec, exec, s[46:47]
	v_mul_f32_e32 v0, v7, v0
	s_nop 1
	v_mov_b32_dpp v1, v0 quad_perm:[1,0,3,2] row_mask:0xf bank_mask:0xf
	s_nop 0
	s_and_saveexec_b64 s[46:47], s[4:5]
	s_cbranch_execz .LBB0_828
	s_waitcnt lgkmcnt(0)
	v_cvt_pk_bf16_f32 v2, v0, v1
	v_add_co_u32_e32 v0, vcc, 0xb000, v96
	s_nop 1
	v_addc_co_u32_e32 v1, vcc, 0, v97, vcc
	global_store_dword v[0:1], v2, off offset:192
.LBB0_828:
	s_or_b64 exec, exec, s[46:47]
	v_add_f32_e32 v0, v72, v76
	v_rcp_f32_e32 v0, v0
	s_waitcnt lgkmcnt(0)
	v_mul_f32_e32 v1, v56, v0
	s_nop 1
	v_mov_b32_dpp v2, v1 quad_perm:[1,0,3,2] row_mask:0xf bank_mask:0xf
	s_nop 0
	s_and_saveexec_b64 s[46:47], s[4:5]
	s_cbranch_execz .LBB0_830
	s_waitcnt lgkmcnt(0)
	v_cvt_pk_bf16_f32 v1, v1, v2
	v_add_co_u32_e32 v2, vcc, 0x10000, v96
	s_nop 1
	v_addc_co_u32_e32 v3, vcc, 0, v97, vcc
	global_store_dword v[2:3], v1, off
.LBB0_830:
	s_or_b64 exec, exec, s[46:47]
	v_mul_f32_e32 v1, v40, v0
	s_waitcnt lgkmcnt(0)
	s_nop 1
	v_mov_b32_dpp v2, v1 quad_perm:[1,0,3,2] row_mask:0xf bank_mask:0xf
	s_nop 0
	s_and_saveexec_b64 s[46:47], s[4:5]
	s_cbranch_execz .LBB0_832
	s_waitcnt lgkmcnt(0)
	v_cvt_pk_bf16_f32 v1, v1, v2
	v_add_co_u32_e32 v2, vcc, 0x10000, v96
	s_nop 1
	v_addc_co_u32_e32 v3, vcc, 0, v97, vcc
	global_store_dword v[2:3], v1, off offset:64
.LBB0_832:
	s_or_b64 exec, exec, s[46:47]
	v_mul_f32_e32 v1, v24, v0
	s_waitcnt lgkmcnt(0)
	s_nop 1
	v_mov_b32_dpp v2, v1 quad_perm:[1,0,3,2] row_mask:0xf bank_mask:0xf
	s_nop 0
	s_and_saveexec_b64 s[46:47], s[4:5]
	s_cbranch_execz .LBB0_834
	s_waitcnt lgkmcnt(0)
	v_cvt_pk_bf16_f32 v1, v1, v2
	v_add_co_u32_e32 v2, vcc, 0x10000, v96
	s_nop 1
	v_addc_co_u32_e32 v3, vcc, 0, v97, vcc
	global_store_dword v[2:3], v1, off offset:128
.LBB0_834:
	s_or_b64 exec, exec, s[46:47]
	v_mul_f32_e32 v0, v8, v0
	s_nop 1
	v_mov_b32_dpp v1, v0 quad_perm:[1,0,3,2] row_mask:0xf bank_mask:0xf
	s_nop 0
	s_and_saveexec_b64 s[46:47], s[4:5]
	s_cbranch_execz .LBB0_836
	s_waitcnt lgkmcnt(0)
	v_cvt_pk_bf16_f32 v2, v0, v1
	v_add_co_u32_e32 v0, vcc, 0x10000, v96
	s_nop 1
	v_addc_co_u32_e32 v1, vcc, 0, v97, vcc
	global_store_dword v[0:1], v2, off offset:192
.LBB0_836:
	s_or_b64 exec, exec, s[46:47]
	v_add_f32_e32 v0, v73, v77
	v_rcp_f32_e32 v0, v0
	s_waitcnt lgkmcnt(0)
	v_mul_f32_e32 v1, v57, v0
	s_nop 1
	v_mov_b32_dpp v2, v1 quad_perm:[1,0,3,2] row_mask:0xf bank_mask:0xf
	s_nop 0
	s_and_saveexec_b64 s[46:47], s[4:5]
	s_cbranch_execz .LBB0_838
	s_waitcnt lgkmcnt(0)
	v_cvt_pk_bf16_f32 v1, v1, v2
	v_add_co_u32_e32 v2, vcc, 0x11000, v96
	s_nop 1
	v_addc_co_u32_e32 v3, vcc, 0, v97, vcc
	global_store_dword v[2:3], v1, off
.LBB0_838:
	s_or_b64 exec, exec, s[46:47]
	v_mul_f32_e32 v1, v41, v0
	s_waitcnt lgkmcnt(0)
	s_nop 1
	v_mov_b32_dpp v2, v1 quad_perm:[1,0,3,2] row_mask:0xf bank_mask:0xf
	s_nop 0
	s_and_saveexec_b64 s[46:47], s[4:5]
	s_cbranch_execz .LBB0_840
	s_waitcnt lgkmcnt(0)
	v_cvt_pk_bf16_f32 v1, v1, v2
	v_add_co_u32_e32 v2, vcc, 0x11000, v96
	s_nop 1
	v_addc_co_u32_e32 v3, vcc, 0, v97, vcc
	global_store_dword v[2:3], v1, off offset:64
.LBB0_840:
	s_or_b64 exec, exec, s[46:47]
	v_mul_f32_e32 v1, v25, v0
	s_waitcnt lgkmcnt(0)
	s_nop 1
	v_mov_b32_dpp v2, v1 quad_perm:[1,0,3,2] row_mask:0xf bank_mask:0xf
	s_nop 0
	s_and_saveexec_b64 s[46:47], s[4:5]
	s_cbranch_execz .LBB0_842
	s_waitcnt lgkmcnt(0)
	v_cvt_pk_bf16_f32 v1, v1, v2
	v_add_co_u32_e32 v2, vcc, 0x11000, v96
	s_nop 1
	v_addc_co_u32_e32 v3, vcc, 0, v97, vcc
	global_store_dword v[2:3], v1, off offset:128
.LBB0_842:
	s_or_b64 exec, exec, s[46:47]
	v_mul_f32_e32 v0, v9, v0
	s_nop 1
	v_mov_b32_dpp v1, v0 quad_perm:[1,0,3,2] row_mask:0xf bank_mask:0xf
	s_nop 0
	s_and_saveexec_b64 s[46:47], s[4:5]
	s_cbranch_execz .LBB0_844
	s_waitcnt lgkmcnt(0)
	v_cvt_pk_bf16_f32 v2, v0, v1
	v_add_co_u32_e32 v0, vcc, 0x11000, v96
	s_nop 1
	v_addc_co_u32_e32 v1, vcc, 0, v97, vcc
	global_store_dword v[0:1], v2, off offset:192
.LBB0_844:
	s_or_b64 exec, exec, s[46:47]
	v_add_f32_e32 v0, v74, v78
	v_rcp_f32_e32 v0, v0
	s_waitcnt lgkmcnt(0)
	v_mul_f32_e32 v1, v58, v0
	s_nop 1
	v_mov_b32_dpp v2, v1 quad_perm:[1,0,3,2] row_mask:0xf bank_mask:0xf
	s_nop 0
	s_and_saveexec_b64 s[46:47], s[4:5]
	s_cbranch_execz .LBB0_846
	s_waitcnt lgkmcnt(0)
	v_cvt_pk_bf16_f32 v1, v1, v2
	v_add_co_u32_e32 v2, vcc, 0x12000, v96
	s_nop 1
	v_addc_co_u32_e32 v3, vcc, 0, v97, vcc
	global_store_dword v[2:3], v1, off
.LBB0_846:
	s_or_b64 exec, exec, s[46:47]
	v_mul_f32_e32 v1, v42, v0
	s_waitcnt lgkmcnt(0)
	s_nop 1
	v_mov_b32_dpp v2, v1 quad_perm:[1,0,3,2] row_mask:0xf bank_mask:0xf
	s_nop 0
	s_and_saveexec_b64 s[46:47], s[4:5]
	s_cbranch_execz .LBB0_848
	s_waitcnt lgkmcnt(0)
	v_cvt_pk_bf16_f32 v1, v1, v2
	v_add_co_u32_e32 v2, vcc, 0x12000, v96
	s_nop 1
	v_addc_co_u32_e32 v3, vcc, 0, v97, vcc
	global_store_dword v[2:3], v1, off offset:64
.LBB0_848:
	s_or_b64 exec, exec, s[46:47]
	v_mul_f32_e32 v1, v26, v0
	s_waitcnt lgkmcnt(0)
	s_nop 1
	v_mov_b32_dpp v2, v1 quad_perm:[1,0,3,2] row_mask:0xf bank_mask:0xf
	s_nop 0
	s_and_saveexec_b64 s[46:47], s[4:5]
	s_cbranch_execz .LBB0_850
	s_waitcnt lgkmcnt(0)
	v_cvt_pk_bf16_f32 v1, v1, v2
	v_add_co_u32_e32 v2, vcc, 0x12000, v96
	s_nop 1
	v_addc_co_u32_e32 v3, vcc, 0, v97, vcc
	global_store_dword v[2:3], v1, off offset:128
.LBB0_850:
	s_or_b64 exec, exec, s[46:47]
	v_mul_f32_e32 v0, v10, v0
	s_nop 1
	v_mov_b32_dpp v1, v0 quad_perm:[1,0,3,2] row_mask:0xf bank_mask:0xf
	s_nop 0
	s_and_saveexec_b64 s[46:47], s[4:5]
	s_cbranch_execz .LBB0_852
	s_waitcnt lgkmcnt(0)
	v_cvt_pk_bf16_f32 v2, v0, v1
	v_add_co_u32_e32 v0, vcc, 0x12000, v96
	s_nop 1
	v_addc_co_u32_e32 v1, vcc, 0, v97, vcc
	global_store_dword v[0:1], v2, off offset:192
.LBB0_852:
	s_or_b64 exec, exec, s[46:47]
	v_add_f32_e32 v0, v75, v79
	v_rcp_f32_e32 v0, v0
	s_waitcnt lgkmcnt(0)
	v_mul_f32_e32 v1, v59, v0
	s_nop 1
	v_mov_b32_dpp v2, v1 quad_perm:[1,0,3,2] row_mask:0xf bank_mask:0xf
	s_nop 0
	s_and_saveexec_b64 s[46:47], s[4:5]
	s_cbranch_execz .LBB0_854
	s_waitcnt lgkmcnt(0)
	v_cvt_pk_bf16_f32 v1, v1, v2
	v_add_co_u32_e32 v2, vcc, 0x13000, v96
	s_nop 1
	v_addc_co_u32_e32 v3, vcc, 0, v97, vcc
	global_store_dword v[2:3], v1, off
.LBB0_854:
	s_or_b64 exec, exec, s[46:47]
	v_mul_f32_e32 v1, v43, v0
	s_waitcnt lgkmcnt(0)
	s_nop 1
	v_mov_b32_dpp v2, v1 quad_perm:[1,0,3,2] row_mask:0xf bank_mask:0xf
	s_nop 0
	s_and_saveexec_b64 s[46:47], s[4:5]
	s_cbranch_execz .LBB0_856
	s_waitcnt lgkmcnt(0)
	v_cvt_pk_bf16_f32 v1, v1, v2
	v_add_co_u32_e32 v2, vcc, 0x13000, v96
	s_nop 1
	v_addc_co_u32_e32 v3, vcc, 0, v97, vcc
	global_store_dword v[2:3], v1, off offset:64
.LBB0_856:
	s_or_b64 exec, exec, s[46:47]
	v_mul_f32_e32 v1, v27, v0
	s_waitcnt lgkmcnt(0)
	s_nop 1
	v_mov_b32_dpp v2, v1 quad_perm:[1,0,3,2] row_mask:0xf bank_mask:0xf
	s_nop 0
	s_and_saveexec_b64 s[46:47], s[4:5]
	s_cbranch_execz .LBB0_858
	s_waitcnt lgkmcnt(0)
	v_cvt_pk_bf16_f32 v1, v1, v2
	v_add_co_u32_e32 v2, vcc, 0x13000, v96
	s_nop 1
	v_addc_co_u32_e32 v3, vcc, 0, v97, vcc
	global_store_dword v[2:3], v1, off offset:128
.LBB0_858:
	s_or_b64 exec, exec, s[46:47]
	v_mul_f32_e32 v0, v11, v0
	s_nop 1
	v_mov_b32_dpp v1, v0 quad_perm:[1,0,3,2] row_mask:0xf bank_mask:0xf
	s_nop 0
	s_and_saveexec_b64 s[46:47], s[4:5]
	s_cbranch_execz .LBB0_860
	s_waitcnt lgkmcnt(0)
	v_cvt_pk_bf16_f32 v2, v0, v1
	v_add_co_u32_e32 v0, vcc, 0x13000, v96
	s_nop 1
	v_addc_co_u32_e32 v1, vcc, 0, v97, vcc
	global_store_dword v[0:1], v2, off offset:192
.LBB0_860:
	s_or_b64 exec, exec, s[46:47]
	v_add_f32_e32 v0, v64, v68
	v_rcp_f32_e32 v0, v0
	s_waitcnt lgkmcnt(0)
	v_mul_f32_e32 v1, v60, v0
	s_nop 1
	v_mov_b32_dpp v2, v1 quad_perm:[1,0,3,2] row_mask:0xf bank_mask:0xf
	s_nop 0
	s_and_saveexec_b64 s[46:47], s[4:5]
	s_cbranch_execz .LBB0_862
	s_waitcnt lgkmcnt(0)
	v_cvt_pk_bf16_f32 v1, v1, v2
	v_add_co_u32_e32 v2, vcc, 0x18000, v96
	s_nop 1
	v_addc_co_u32_e32 v3, vcc, 0, v97, vcc
	global_store_dword v[2:3], v1, off
.LBB0_862:
	s_or_b64 exec, exec, s[46:47]
	v_mul_f32_e32 v1, v44, v0
	s_waitcnt lgkmcnt(0)
	s_nop 1
	v_mov_b32_dpp v2, v1 quad_perm:[1,0,3,2] row_mask:0xf bank_mask:0xf
	s_nop 0
	s_and_saveexec_b64 s[46:47], s[4:5]
	s_cbranch_execz .LBB0_864
	s_waitcnt lgkmcnt(0)
	v_cvt_pk_bf16_f32 v1, v1, v2
	v_add_co_u32_e32 v2, vcc, 0x18000, v96
	s_nop 1
	v_addc_co_u32_e32 v3, vcc, 0, v97, vcc
	global_store_dword v[2:3], v1, off offset:64
.LBB0_864:
	s_or_b64 exec, exec, s[46:47]
	v_mul_f32_e32 v1, v28, v0
	s_waitcnt lgkmcnt(0)
	s_nop 1
	v_mov_b32_dpp v2, v1 quad_perm:[1,0,3,2] row_mask:0xf bank_mask:0xf
	s_nop 0
	s_and_saveexec_b64 s[46:47], s[4:5]
	s_cbranch_execz .LBB0_866
	s_waitcnt lgkmcnt(0)
	v_cvt_pk_bf16_f32 v1, v1, v2
	v_add_co_u32_e32 v2, vcc, 0x18000, v96
	s_nop 1
	v_addc_co_u32_e32 v3, vcc, 0, v97, vcc
	global_store_dword v[2:3], v1, off offset:128
.LBB0_866:
	s_or_b64 exec, exec, s[46:47]
	v_mul_f32_e32 v0, v12, v0
	s_nop 1
	v_mov_b32_dpp v1, v0 quad_perm:[1,0,3,2] row_mask:0xf bank_mask:0xf
	s_nop 0
	s_and_saveexec_b64 s[46:47], s[4:5]
	s_cbranch_execz .LBB0_868
	s_waitcnt lgkmcnt(0)
	v_cvt_pk_bf16_f32 v2, v0, v1
	v_add_co_u32_e32 v0, vcc, 0x18000, v96
	s_nop 1
	v_addc_co_u32_e32 v1, vcc, 0, v97, vcc
	global_store_dword v[0:1], v2, off offset:192
.LBB0_868:
	s_or_b64 exec, exec, s[46:47]
	v_add_f32_e32 v0, v65, v69
	v_rcp_f32_e32 v0, v0
	s_waitcnt lgkmcnt(0)
	v_mul_f32_e32 v1, v61, v0
	s_nop 1
	v_mov_b32_dpp v2, v1 quad_perm:[1,0,3,2] row_mask:0xf bank_mask:0xf
	s_nop 0
	s_and_saveexec_b64 s[46:47], s[4:5]
	s_cbranch_execz .LBB0_870
	s_waitcnt lgkmcnt(0)
	v_cvt_pk_bf16_f32 v1, v1, v2
	v_add_co_u32_e32 v2, vcc, 0x19000, v96
	s_nop 1
	v_addc_co_u32_e32 v3, vcc, 0, v97, vcc
	global_store_dword v[2:3], v1, off
.LBB0_870:
	s_or_b64 exec, exec, s[46:47]
	v_mul_f32_e32 v1, v45, v0
	s_waitcnt lgkmcnt(0)
	s_nop 1
	v_mov_b32_dpp v2, v1 quad_perm:[1,0,3,2] row_mask:0xf bank_mask:0xf
	s_nop 0
	s_and_saveexec_b64 s[46:47], s[4:5]
	s_cbranch_execz .LBB0_872
	s_waitcnt lgkmcnt(0)
	v_cvt_pk_bf16_f32 v1, v1, v2
	v_add_co_u32_e32 v2, vcc, 0x19000, v96
	s_nop 1
	v_addc_co_u32_e32 v3, vcc, 0, v97, vcc
	global_store_dword v[2:3], v1, off offset:64
.LBB0_872:
	s_or_b64 exec, exec, s[46:47]
	v_mul_f32_e32 v1, v29, v0
	s_waitcnt lgkmcnt(0)
	s_nop 1
	v_mov_b32_dpp v2, v1 quad_perm:[1,0,3,2] row_mask:0xf bank_mask:0xf
	s_nop 0
	s_and_saveexec_b64 s[46:47], s[4:5]
	s_cbranch_execz .LBB0_874
	s_waitcnt lgkmcnt(0)
	v_cvt_pk_bf16_f32 v1, v1, v2
	v_add_co_u32_e32 v2, vcc, 0x19000, v96
	s_nop 1
	v_addc_co_u32_e32 v3, vcc, 0, v97, vcc
	global_store_dword v[2:3], v1, off offset:128
.LBB0_874:
	s_or_b64 exec, exec, s[46:47]
	v_mul_f32_e32 v0, v13, v0
	s_nop 1
	v_mov_b32_dpp v1, v0 quad_perm:[1,0,3,2] row_mask:0xf bank_mask:0xf
	s_nop 0
	s_and_saveexec_b64 s[46:47], s[4:5]
	s_cbranch_execz .LBB0_876
	s_waitcnt lgkmcnt(0)
	v_cvt_pk_bf16_f32 v2, v0, v1
	v_add_co_u32_e32 v0, vcc, 0x19000, v96
	s_nop 1
	v_addc_co_u32_e32 v1, vcc, 0, v97, vcc
	global_store_dword v[0:1], v2, off offset:192
.LBB0_876:
	s_or_b64 exec, exec, s[46:47]
	v_add_f32_e32 v0, v66, v70
	v_rcp_f32_e32 v0, v0
	s_waitcnt lgkmcnt(0)
	v_mul_f32_e32 v1, v62, v0
	s_nop 1
	v_mov_b32_dpp v2, v1 quad_perm:[1,0,3,2] row_mask:0xf bank_mask:0xf
	s_nop 0
	s_and_saveexec_b64 s[46:47], s[4:5]
	s_cbranch_execz .LBB0_878
	s_waitcnt lgkmcnt(0)
	v_cvt_pk_bf16_f32 v1, v1, v2
	v_add_co_u32_e32 v2, vcc, 0x1a000, v96
	s_nop 1
	v_addc_co_u32_e32 v3, vcc, 0, v97, vcc
	global_store_dword v[2:3], v1, off
.LBB0_878:
	s_or_b64 exec, exec, s[46:47]
	v_mul_f32_e32 v1, v46, v0
	s_waitcnt lgkmcnt(0)
	s_nop 1
	v_mov_b32_dpp v2, v1 quad_perm:[1,0,3,2] row_mask:0xf bank_mask:0xf
	s_nop 0
	s_and_saveexec_b64 s[46:47], s[4:5]
	s_cbranch_execz .LBB0_880
	s_waitcnt lgkmcnt(0)
	v_cvt_pk_bf16_f32 v1, v1, v2
	v_add_co_u32_e32 v2, vcc, 0x1a000, v96
	s_nop 1
	v_addc_co_u32_e32 v3, vcc, 0, v97, vcc
	global_store_dword v[2:3], v1, off offset:64
.LBB0_880:
	s_or_b64 exec, exec, s[46:47]
	v_mul_f32_e32 v1, v30, v0
	s_waitcnt lgkmcnt(0)
	s_nop 1
	v_mov_b32_dpp v2, v1 quad_perm:[1,0,3,2] row_mask:0xf bank_mask:0xf
	s_nop 0
	s_and_saveexec_b64 s[46:47], s[4:5]
	s_cbranch_execz .LBB0_882
	s_waitcnt lgkmcnt(0)
	v_cvt_pk_bf16_f32 v1, v1, v2
	v_add_co_u32_e32 v2, vcc, 0x1a000, v96
	s_nop 1
	v_addc_co_u32_e32 v3, vcc, 0, v97, vcc
	global_store_dword v[2:3], v1, off offset:128
.LBB0_882:
	s_or_b64 exec, exec, s[46:47]
	v_mul_f32_e32 v0, v14, v0
	s_nop 1
	v_mov_b32_dpp v1, v0 quad_perm:[1,0,3,2] row_mask:0xf bank_mask:0xf
	s_nop 0
	s_and_saveexec_b64 s[46:47], s[4:5]
	s_cbranch_execz .LBB0_884
	s_waitcnt lgkmcnt(0)
	v_cvt_pk_bf16_f32 v2, v0, v1
	v_add_co_u32_e32 v0, vcc, 0x1a000, v96
	s_nop 1
	v_addc_co_u32_e32 v1, vcc, 0, v97, vcc
	global_store_dword v[0:1], v2, off offset:192
.LBB0_884:
	s_or_b64 exec, exec, s[46:47]
	v_add_f32_e32 v0, v67, v71
	v_rcp_f32_e32 v0, v0
	s_waitcnt lgkmcnt(0)
	v_mul_f32_e32 v1, v63, v0
	s_nop 1
	v_mov_b32_dpp v2, v1 quad_perm:[1,0,3,2] row_mask:0xf bank_mask:0xf
	s_nop 0
	s_and_saveexec_b64 s[46:47], s[4:5]
	s_cbranch_execz .LBB0_886
	s_waitcnt lgkmcnt(0)
	v_cvt_pk_bf16_f32 v1, v1, v2
	v_add_co_u32_e32 v2, vcc, 0x1b000, v96
	s_nop 1
	v_addc_co_u32_e32 v3, vcc, 0, v97, vcc
	global_store_dword v[2:3], v1, off
.LBB0_886:
	s_or_b64 exec, exec, s[46:47]
	v_mul_f32_e32 v1, v47, v0
	s_waitcnt lgkmcnt(0)
	s_nop 1
	v_mov_b32_dpp v2, v1 quad_perm:[1,0,3,2] row_mask:0xf bank_mask:0xf
	s_nop 0
	s_and_saveexec_b64 s[46:47], s[4:5]
	s_cbranch_execz .LBB0_888
	s_waitcnt lgkmcnt(0)
	v_cvt_pk_bf16_f32 v1, v1, v2
	v_add_co_u32_e32 v2, vcc, 0x1b000, v96
	s_nop 1
	v_addc_co_u32_e32 v3, vcc, 0, v97, vcc
	global_store_dword v[2:3], v1, off offset:64
.LBB0_888:
	s_or_b64 exec, exec, s[46:47]
	v_mul_f32_e32 v1, v31, v0
	s_waitcnt lgkmcnt(0)
	s_nop 1
	v_mov_b32_dpp v2, v1 quad_perm:[1,0,3,2] row_mask:0xf bank_mask:0xf
	s_nop 0
	s_and_saveexec_b64 s[46:47], s[4:5]
	s_cbranch_execz .LBB0_890
	s_waitcnt lgkmcnt(0)
	v_cvt_pk_bf16_f32 v1, v1, v2
	v_add_co_u32_e32 v2, vcc, 0x1b000, v96
	s_nop 1
	v_addc_co_u32_e32 v3, vcc, 0, v97, vcc
	global_store_dword v[2:3], v1, off offset:128
.LBB0_890:
	s_or_b64 exec, exec, s[46:47]
	v_mul_f32_e32 v0, v15, v0
	s_nop 1
	v_mov_b32_dpp v1, v0 quad_perm:[1,0,3,2] row_mask:0xf bank_mask:0xf
	s_nop 0
	s_and_saveexec_b64 s[46:47], s[4:5]
	s_cbranch_execz .LBB0_721
	s_waitcnt lgkmcnt(0)
	v_cvt_pk_bf16_f32 v2, v0, v1
	v_add_co_u32_e32 v0, vcc, 0x1b000, v96
	s_nop 1
	v_addc_co_u32_e32 v1, vcc, 0, v97, vcc
	global_store_dword v[0:1], v2, off offset:192
	s_branch .LBB0_721
